# P3c groupnorm loop: hoist all 4 tokens' loads to item start (one memory round trip per item instead of four)
# speedup vs baseline: 1.0099x; 1.0099x over previous
; __device__ __forceinline__ f32x4 bf4(v2u u) { return (f32x4){bflo(u.x), bfhi(u.x), bflo(u.y), bfhi(u.y)}; }
; __device__ __forceinline__ v2u pk4(f32x4 v) { v2u o; o.x = pk2(v.x, v.y); o.y = pk2(v.z, v.w); return o; }
; __device__ __forceinline__ void p3_gn_chunk(const Args& a, int ch, int lane) {
;     const int n = lane & 15, rg = lane >> 4, head = ch & 15, c0 = head * 64 + 4 * n; const int t0 = (ch >> 4) * 16 + 4 * rg;
;     const bf16* YR = (const bf16*)(a.ws + WS_YR); const bf16* ZB = (const bf16*)(a.ws + WS_ZB); bf16* Y = (bf16*)(a.ws + WS_XN); const float* RK = (const float*)(a.ws + WS_RK);
;     const f32x4 lw = ld4(a.in[16] + c0), lb = ld4(a.in[17] + c0);
;     f32x4 vimg[4];
; #pragma unroll
;     for (int cb = 0; cb < 4; ++cb) vimg[cb] = bf4(*(const v2u*)(a.ws + WS_VS + (size_t)ch * 2048 + cb * 512 + lane * 8));
; #pragma unroll
;     for (int e = 0; e < 4; ++e) { const int t = t0 + e;
;         f32x4 y = bf4(*(const v2u*)(YR + (size_t)t * 1024 + c0));
;         const f32x4 g = bf4(*(const v2u*)(ZB + (size_t)t * 5120 + 4096 + c0)); const float rk = RK[(size_t)t * 16 + head];
;         const float mean = row16_sum((y.x + y.y) + (y.z + y.w)) * (1.f / 64.f);
;         y = y - mean;
;         const float rstd = __builtin_amdgcn_rsqf(row16_sum((y.x * y.x + y.y * y.y) + (y.z * y.z + y.w * y.w)) * (1.f / 64.f) + GN_EPS);
;         const f32x4 v = {vimg[0][e], vimg[1][e], vimg[2][e], vimg[3][e]};
;         f32x4 o = y * rstd * lw + lb + v * rk;
; #pragma unroll
;         for (int k = 0; k < 4; ++k) o[k] *= g[k] * __builtin_amdgcn_rcpf(1.f + __expf(-g[k]));
;         *(v2u*)(Y + (size_t)t * 2048 + c0) = pk4(o); }
; __global__ void __launch_bounds__(NTHR, 2) hybrid_fwd(Args args) {
;     ...
;     for (int ch = F.gw; ch < (T / 16) * NH; ch += F.NGW) p3_gn_chunk(args, ch, F.lane);
.LBB0_640:
	s_and_b32 s4, s8, 15
	s_and_b32 s5, s8, -16
	v_lshl_or_b32 v0, s4, 6, v30
	v_add_u32_e32 v26, s5, v31
	s_lshl_b32 s4, s4, 2
	v_lshlrev_b32_e32 v10, 1, v0
	v_ashrrev_i32_e32 v27, 31, v26
	v_mad_i64_i32 v[28:29], s[10:11], v26, s6, v[12:13]
	s_add_u32 s4, s2, s4
	v_or_b32_e32 v34, 1, v26
	v_or_b32_e32 v36, 2, v26
	v_or_b32_e32 v22, 3, v26
	v_lshl_add_u64 v[38:39], s[72:73], 0, v[10:11]
	v_lshlrev_b64 v[40:41], 11, v[26:27]
	v_lshl_add_u64 v[28:29], v[28:29], 0, v[10:11]
	v_lshlrev_b32_e32 v23, 2, v0
	s_addc_u32 s5, s3, 0
	v_lshlrev_b64 v[42:43], 6, v[26:27]
	v_mad_i64_i32 v[44:45], s[10:11], v34, s6, v[12:13]
	v_mad_i64_i32 v[46:47], s[10:11], v36, s6, v[12:13]
	v_mad_i64_i32 v[48:49], s[10:11], v22, s6, v[12:13]
	v_lshl_add_u64 v[40:41], v[38:39], 0, v[40:41]
	v_add_co_u32_e32 v28, vcc, s7, v28
	global_load_dwordx2 v[14:15], v[8:9], off
	global_load_dwordx2 v[16:17], v[8:9], off offset:512
	global_load_dwordx2 v[18:19], v[8:9], off offset:1024
	global_load_dwordx2 v[20:21], v[8:9], off offset:1536
	global_load_dwordx4 v[0:3], v23, s[12:13]
	global_load_dwordx4 v[4:7], v23, s[14:15]
	v_lshl_add_u64 v[24:25], s[60:61], 0, v[10:11]
	v_addc_co_u32_e32 v29, vcc, 0, v29, vcc
	v_lshl_add_u64 v[42:43], s[4:5], 0, v[42:43]
	v_lshl_add_u64 v[44:45], v[44:45], 0, v[10:11]
	v_lshl_add_u64 v[46:47], v[46:47], 0, v[10:11]
	v_lshl_add_u64 v[48:49], v[48:49], 0, v[10:11]
	global_load_dwordx2 v[40:41], v[40:41], off
	s_nop 0
	global_load_dwordx2 v[60:61], v[28:29], off
	global_load_dword v10, v[42:43], off
	v_ashrrev_i32_e32 v35, 31, v34
	v_ashrrev_i32_e32 v37, 31, v36
	v_lshlrev_b64 v[50:51], 11, v[34:35]
	v_lshlrev_b64 v[52:53], 6, v[34:35]
	v_lshlrev_b64 v[54:55], 11, v[36:37]
	v_lshlrev_b64 v[56:57], 6, v[36:37]
	v_add_co_u32_e32 v42, vcc, s7, v44
	v_lshl_add_u64 v[28:29], v[38:39], 0, v[50:51]
	s_nop 0
	v_addc_co_u32_e32 v43, vcc, 0, v45, vcc
	v_lshl_add_u64 v[44:45], s[4:5], 0, v[52:53]
	v_lshl_add_u64 v[50:51], v[38:39], 0, v[54:55]
	v_lshl_add_u64 v[52:53], s[4:5], 0, v[56:57]
	v_lshlrev_b64 v[26:27], 12, v[26:27]
	v_lshl_add_u64 v[26:27], v[24:25], 0, v[26:27]
	v_lshlrev_b64 v[34:35], 12, v[34:35]
	v_lshl_add_u64 v[34:35], v[24:25], 0, v[34:35]
	v_add_co_u32_e32 v46, vcc, s7, v46
	v_ashrrev_i32_e32 v23, 31, v22
	s_nop 0
	v_addc_co_u32_e32 v47, vcc, 0, v47, vcc
	v_lshlrev_b64 v[58:59], 11, v[22:23]
	v_lshl_add_u64 v[38:39], v[38:39], 0, v[58:59]
	v_lshlrev_b64 v[36:37], 12, v[36:37]
	v_lshl_add_u64 v[36:37], v[24:25], 0, v[36:37]
	v_add_co_u32_e32 v48, vcc, s7, v48
	s_add_i32 s8, s8, s42
	s_nop 0
	v_addc_co_u32_e32 v49, vcc, 0, v49, vcc
	v_lshl_add_u64 v[8:9], v[8:9], 0, s[0:1]
	s_cmpk_gt_i32 s8, 0x3fff
	v_lshlrev_b64 v[118:119], 6, v[22:23]
	global_load_dwordx2 v[100:101], v[28:29], off
	global_load_dwordx2 v[102:103], v[42:43], off
	global_load_dword v104, v[44:45], off
	v_lshl_add_u64 v[118:119], s[4:5], 0, v[118:119]
	global_load_dwordx2 v[106:107], v[50:51], off
	global_load_dwordx2 v[108:109], v[46:47], off
	global_load_dword v110, v[52:53], off
	global_load_dwordx2 v[112:113], v[38:39], off
	global_load_dwordx2 v[114:115], v[48:49], off
	global_load_dword v116, v[118:119], off
	s_waitcnt vmcnt(17)
	v_lshlrev_b32_e32 v54, 16, v14
	v_and_b32_e32 v56, 0xffff0000, v14
	s_waitcnt vmcnt(16)
	v_lshlrev_b32_e32 v55, 16, v16
	v_and_b32_e32 v57, 0xffff0000, v16
	s_waitcnt vmcnt(15)
	v_lshlrev_b32_e32 v62, 16, v18
	v_and_b32_e32 v64, 0xffff0000, v18
	s_waitcnt vmcnt(14)
	v_lshlrev_b32_e32 v63, 16, v20
	v_and_b32_e32 v65, 0xffff0000, v20
	v_lshlrev_b32_e32 v58, 16, v15
	v_lshlrev_b32_e32 v59, 16, v17
	s_waitcnt vmcnt(11)
	v_lshlrev_b32_e32 v69, 16, v41
	v_lshlrev_b32_e32 v68, 16, v40
	v_and_b32_e32 v41, 0xffff0000, v41
	v_and_b32_e32 v40, 0xffff0000, v40
	v_pk_add_f32 v[72:73], v[68:69], v[40:41]
	s_waitcnt vmcnt(10)
	v_lshlrev_b32_e32 v70, 16, v60
	v_add_f32_e32 v33, v72, v73
	v_mul_f32_e32 v14, 0xbfb8aa3b, v70
	v_exp_f32_e32 v14, v14
	v_add_f32_dpp v33, v33, v33 quad_perm:[1,0,3,2] row_mask:0xf bank_mask:0xf bound_ctrl:1
	v_and_b32_e32 v71, 0xffff0000, v60
	v_lshlrev_b32_e32 v60, 16, v61
	v_add_f32_dpp v33, v33, v33 quad_perm:[2,3,0,1] row_mask:0xf bank_mask:0xf bound_ctrl:1
	v_add_f32_e32 v14, 1.0, v14
	v_rcp_f32_e32 v72, v14
	v_add_f32_dpp v33, v33, v33 row_half_mirror row_mask:0xf bank_mask:0xf bound_ctrl:1
	v_and_b32_e32 v61, 0xffff0000, v61
	v_mul_f32_e32 v16, 0xbfb8aa3b, v71
	v_add_f32_dpp v33, v33, v33 row_mirror row_mask:0xf bank_mask:0xf bound_ctrl:1
	v_fmac_f32_e32 v40, 0xbc800000, v33
	v_fmac_f32_e32 v41, 0xbc800000, v33
	v_fmac_f32_e32 v69, 0xbc800000, v33
	v_fmac_f32_e32 v68, 0xbc800000, v33
	v_mov_b32_e32 v76, v69
	v_mov_b32_e32 v77, v41
	v_mov_b32_e32 v69, v40
	v_pk_mul_f32 v[40:41], v[76:77], v[76:77]
	v_pk_mul_f32 v[78:79], v[68:69], v[68:69]
	v_mul_f32_e32 v18, 0xbfb8aa3b, v60
	v_pk_mov_b32 v[80:81], v[78:79], v[40:41] op_sel:[1,0]
	v_mov_b32_e32 v79, v41
	v_pk_add_f32 v[40:41], v[80:81], v[78:79]
	v_mul_f32_e32 v20, 0xbfb8aa3b, v61
	v_add_f32_e32 v14, v40, v41
	v_exp_f32_e32 v16, v16
	v_exp_f32_e32 v18, v18
	v_add_f32_dpp v14, v14, v14 quad_perm:[1,0,3,2] row_mask:0xf bank_mask:0xf bound_ctrl:1
	v_exp_f32_e32 v20, v20
	v_add_f32_e32 v16, 1.0, v16
	v_add_f32_dpp v14, v14, v14 quad_perm:[2,3,0,1] row_mask:0xf bank_mask:0xf bound_ctrl:1
	v_add_f32_e32 v18, 1.0, v18
	v_add_f32_e32 v20, 1.0, v20
	v_add_f32_dpp v14, v14, v14 row_half_mirror row_mask:0xf bank_mask:0xf bound_ctrl:1
	v_rcp_f32_e32 v73, v16
	v_rcp_f32_e32 v74, v18
	v_add_f32_dpp v14, v14, v14 row_mirror row_mask:0xf bank_mask:0xf bound_ctrl:1
	v_fmamk_f32 v14, v14, 0x3c800000, v32
	v_rsq_f32_e32 v14, v14
	v_rcp_f32_e32 v75, v20
	v_pk_mul_f32 v[70:71], v[72:73], v[70:71]
	v_lshlrev_b32_e32 v66, 16, v19
	v_pk_mul_f32 v[40:41], v[76:77], v[14:15] op_sel_hi:[1,0]
	v_pk_mul_f32 v[68:69], v[68:69], v[14:15] op_sel_hi:[1,0]
	v_pk_fma_f32 v[40:41], v[2:3], v[40:41], v[6:7]
	v_pk_fma_f32 v[68:69], v[0:1], v[68:69], v[4:5]
	v_pk_mul_f32 v[60:61], v[74:75], v[60:61]
	s_waitcnt vmcnt(9)
; __device__ __forceinline__ f32x4 bf4(v2u u) { return (f32x4){bflo(u.x), bfhi(u.x), bflo(u.y), bfhi(u.y)}; }
; __device__ __forceinline__ v2u pk4(f32x4 v) { v2u o; o.x = pk2(v.x, v.y); o.y = pk2(v.z, v.w); return o; }
; __device__ __forceinline__ void p3_gn_chunk(const Args& a, int ch, int lane) {
;     ...
;     for (int e = 0; e < 4; ++e) { const int t = t0 + e;
;         f32x4 y = bf4(*(const v2u*)(YR + (size_t)t * 1024 + c0));
;         const f32x4 g = bf4(*(const v2u*)(ZB + (size_t)t * 5120 + 4096 + c0)); const float rk = RK[(size_t)t * 16 + head];
;         const float mean = row16_sum((y.x + y.y) + (y.z + y.w)) * (1.f / 64.f);
;         y = y - mean;
;         const float rstd = __builtin_amdgcn_rsqf(row16_sum((y.x * y.x + y.y * y.y) + (y.z * y.z + y.w * y.w)) * (1.f / 64.f) + GN_EPS);
;         const f32x4 v = {vimg[0][e], vimg[1][e], vimg[2][e], vimg[3][e]};
;         f32x4 o = y * rstd * lw + lb + v * rk;
; #pragma unroll
;         for (int k = 0; k < 4; ++k) o[k] *= g[k] * __builtin_amdgcn_rcpf(1.f + __expf(-g[k]));
;         *(v2u*)(Y + (size_t)t * 2048 + c0) = pk4(o); }
	v_pk_fma_f32 v[40:41], v[10:11], v[62:63], v[40:41] op_sel_hi:[0,1,1]
	v_pk_fma_f32 v[54:55], v[10:11], v[54:55], v[68:69] op_sel_hi:[0,1,1]
	v_pk_mul_f32 v[54:55], v[70:71], v[54:55]
	v_pk_mul_f32 v[40:41], v[60:61], v[40:41]
	v_cvt_pk_bf16_f32 v54, v54, v55
	v_cvt_pk_bf16_f32 v55, v40, v41
	global_store_dwordx2 v[26:27], v[54:55], off
	s_waitcnt vmcnt(1)
	v_mov_b32_e32 v26, v100
	v_mov_b32_e32 v27, v101
	v_mov_b32_e32 v28, v102
	v_mov_b32_e32 v29, v103
	v_mov_b32_e32 v10, v104
	s_nop 0
	v_lshlrev_b32_e32 v67, 16, v21
	s_nop 0
	v_lshlrev_b32_e32 v41, 16, v27
	v_lshlrev_b32_e32 v40, 16, v26
	v_and_b32_e32 v27, 0xffff0000, v27
	v_and_b32_e32 v26, 0xffff0000, v26
	v_pk_add_f32 v[44:45], v[40:41], v[26:27]
	s_nop 0
	v_lshlrev_b32_e32 v42, 16, v28
	v_add_f32_e32 v33, v44, v45
	v_mul_f32_e32 v14, 0xbfb8aa3b, v42
	v_exp_f32_e32 v14, v14
	v_add_f32_dpp v33, v33, v33 quad_perm:[1,0,3,2] row_mask:0xf bank_mask:0xf bound_ctrl:1
	v_and_b32_e32 v43, 0xffff0000, v28
	v_lshlrev_b32_e32 v28, 16, v29
	v_add_f32_dpp v33, v33, v33 quad_perm:[2,3,0,1] row_mask:0xf bank_mask:0xf bound_ctrl:1
	v_add_f32_e32 v14, 1.0, v14
	v_rcp_f32_e32 v44, v14
	v_add_f32_dpp v33, v33, v33 row_half_mirror row_mask:0xf bank_mask:0xf bound_ctrl:1
	v_and_b32_e32 v29, 0xffff0000, v29
	v_mul_f32_e32 v16, 0xbfb8aa3b, v43
	v_add_f32_dpp v33, v33, v33 row_mirror row_mask:0xf bank_mask:0xf bound_ctrl:1
	v_fmac_f32_e32 v26, 0xbc800000, v33
	v_fmac_f32_e32 v27, 0xbc800000, v33
	v_fmac_f32_e32 v41, 0xbc800000, v33
	v_fmac_f32_e32 v40, 0xbc800000, v33
	v_mov_b32_e32 v60, v41
	v_mov_b32_e32 v61, v27
	v_mov_b32_e32 v41, v26
	v_pk_mul_f32 v[26:27], v[60:61], v[60:61]
	v_pk_mul_f32 v[62:63], v[40:41], v[40:41]
	v_mul_f32_e32 v18, 0xbfb8aa3b, v28
	v_pk_mov_b32 v[68:69], v[62:63], v[26:27] op_sel:[1,0]
	v_mov_b32_e32 v63, v27
	v_pk_add_f32 v[26:27], v[68:69], v[62:63]
	v_mul_f32_e32 v20, 0xbfb8aa3b, v29
	v_add_f32_e32 v14, v26, v27
	v_exp_f32_e32 v16, v16
	v_exp_f32_e32 v18, v18
	v_add_f32_dpp v14, v14, v14 quad_perm:[1,0,3,2] row_mask:0xf bank_mask:0xf bound_ctrl:1
	v_exp_f32_e32 v20, v20
	v_add_f32_e32 v16, 1.0, v16
	v_add_f32_dpp v14, v14, v14 quad_perm:[2,3,0,1] row_mask:0xf bank_mask:0xf bound_ctrl:1
	v_add_f32_e32 v18, 1.0, v18
	v_add_f32_e32 v20, 1.0, v20
	v_add_f32_dpp v14, v14, v14 row_half_mirror row_mask:0xf bank_mask:0xf bound_ctrl:1
	v_rcp_f32_e32 v45, v16
	v_rcp_f32_e32 v54, v18
	v_add_f32_dpp v14, v14, v14 row_mirror row_mask:0xf bank_mask:0xf bound_ctrl:1
	v_fmamk_f32 v14, v14, 0x3c800000, v32
	v_rsq_f32_e32 v14, v14
	v_rcp_f32_e32 v55, v20
	v_pk_mul_f32 v[42:43], v[44:45], v[42:43]
	v_pk_mul_f32 v[26:27], v[60:61], v[14:15] op_sel_hi:[1,0]
	v_pk_mul_f32 v[40:41], v[40:41], v[14:15] op_sel_hi:[1,0]
	v_pk_fma_f32 v[26:27], v[2:3], v[26:27], v[6:7]
	v_pk_fma_f32 v[40:41], v[0:1], v[40:41], v[4:5]
	v_pk_mul_f32 v[28:29], v[54:55], v[28:29]
	s_nop 0
	v_pk_fma_f32 v[26:27], v[10:11], v[64:65], v[26:27] op_sel_hi:[0,1,1]
	v_pk_fma_f32 v[40:41], v[10:11], v[56:57], v[40:41] op_sel_hi:[0,1,1]
	v_pk_mul_f32 v[40:41], v[42:43], v[40:41]
	v_pk_mul_f32 v[26:27], v[28:29], v[26:27]
	v_cvt_pk_bf16_f32 v28, v40, v41
	v_cvt_pk_bf16_f32 v29, v26, v27
	global_store_dwordx2 v[34:35], v[28:29], off
	s_nop 0
	v_mov_b32_e32 v26, v106
	v_mov_b32_e32 v27, v107
	v_mov_b32_e32 v28, v108
	v_mov_b32_e32 v29, v109
	v_mov_b32_e32 v10, v110
	s_nop 0
	s_nop 0
	v_lshlrev_b32_e32 v35, 16, v27
	v_lshlrev_b32_e32 v34, 16, v26
	v_and_b32_e32 v27, 0xffff0000, v27
	v_and_b32_e32 v26, 0xffff0000, v26
	v_pk_add_f32 v[42:43], v[34:35], v[26:27]
	s_nop 0
	v_lshlrev_b32_e32 v40, 16, v28
	v_add_f32_e32 v33, v42, v43
	v_mul_f32_e32 v14, 0xbfb8aa3b, v40
	v_exp_f32_e32 v14, v14
	v_add_f32_dpp v33, v33, v33 quad_perm:[1,0,3,2] row_mask:0xf bank_mask:0xf bound_ctrl:1
	v_and_b32_e32 v41, 0xffff0000, v28
	v_lshlrev_b32_e32 v28, 16, v29
	v_add_f32_dpp v33, v33, v33 quad_perm:[2,3,0,1] row_mask:0xf bank_mask:0xf bound_ctrl:1
	v_add_f32_e32 v14, 1.0, v14
	v_rcp_f32_e32 v42, v14
	v_add_f32_dpp v33, v33, v33 row_half_mirror row_mask:0xf bank_mask:0xf bound_ctrl:1
	v_and_b32_e32 v29, 0xffff0000, v29
	v_mul_f32_e32 v16, 0xbfb8aa3b, v41
	v_add_f32_dpp v33, v33, v33 row_mirror row_mask:0xf bank_mask:0xf bound_ctrl:1
	v_fmac_f32_e32 v26, 0xbc800000, v33
	v_fmac_f32_e32 v27, 0xbc800000, v33
	v_fmac_f32_e32 v35, 0xbc800000, v33
	v_fmac_f32_e32 v34, 0xbc800000, v33
	v_mov_b32_e32 v46, v35
	v_mov_b32_e32 v47, v27
	v_mov_b32_e32 v35, v26
	v_pk_mul_f32 v[26:27], v[46:47], v[46:47]
	v_pk_mul_f32 v[50:51], v[34:35], v[34:35]
	v_mul_f32_e32 v18, 0xbfb8aa3b, v28
	v_pk_mov_b32 v[52:53], v[50:51], v[26:27] op_sel:[1,0]
; __device__ __forceinline__ f32x4 bf4(v2u u) { return (f32x4){bflo(u.x), bfhi(u.x), bflo(u.y), bfhi(u.y)}; }
; __device__ __forceinline__ v2u pk4(f32x4 v) { v2u o; o.x = pk2(v.x, v.y); o.y = pk2(v.z, v.w); return o; }
; __device__ __forceinline__ void p3_gn_chunk(const Args& a, int ch, int lane) {
;     ...
;     for (int e = 0; e < 4; ++e) { const int t = t0 + e;
;         f32x4 y = bf4(*(const v2u*)(YR + (size_t)t * 1024 + c0));
;         const f32x4 g = bf4(*(const v2u*)(ZB + (size_t)t * 5120 + 4096 + c0)); const float rk = RK[(size_t)t * 16 + head];
;         const float mean = row16_sum((y.x + y.y) + (y.z + y.w)) * (1.f / 64.f);
;         y = y - mean;
;         const float rstd = __builtin_amdgcn_rsqf(row16_sum((y.x * y.x + y.y * y.y) + (y.z * y.z + y.w * y.w)) * (1.f / 64.f) + GN_EPS);
;         const f32x4 v = {vimg[0][e], vimg[1][e], vimg[2][e], vimg[3][e]};
;         f32x4 o = y * rstd * lw + lb + v * rk;
; #pragma unroll
;         for (int k = 0; k < 4; ++k) o[k] *= g[k] * __builtin_amdgcn_rcpf(1.f + __expf(-g[k]));
;         *(v2u*)(Y + (size_t)t * 2048 + c0) = pk4(o); }
; __global__ void __launch_bounds__(NTHR, 2) hybrid_fwd(Args args) {
;     ...
;     for (int ch = F.gw; ch < (T / 16) * NH; ch += F.NGW) p3_gn_chunk(args, ch, F.lane);
	v_mov_b32_e32 v51, v27
	v_pk_add_f32 v[26:27], v[52:53], v[50:51]
	v_mul_f32_e32 v20, 0xbfb8aa3b, v29
	v_add_f32_e32 v14, v26, v27
	v_exp_f32_e32 v16, v16
	v_exp_f32_e32 v18, v18
	v_add_f32_dpp v14, v14, v14 quad_perm:[1,0,3,2] row_mask:0xf bank_mask:0xf bound_ctrl:1
	v_exp_f32_e32 v20, v20
	v_add_f32_e32 v16, 1.0, v16
	v_add_f32_dpp v14, v14, v14 quad_perm:[2,3,0,1] row_mask:0xf bank_mask:0xf bound_ctrl:1
	v_add_f32_e32 v18, 1.0, v18
	v_add_f32_e32 v20, 1.0, v20
	v_add_f32_dpp v14, v14, v14 row_half_mirror row_mask:0xf bank_mask:0xf bound_ctrl:1
	v_rcp_f32_e32 v43, v16
	v_rcp_f32_e32 v44, v18
	v_add_f32_dpp v14, v14, v14 row_mirror row_mask:0xf bank_mask:0xf bound_ctrl:1
	v_fmamk_f32 v14, v14, 0x3c800000, v32
	v_rsq_f32_e32 v14, v14
	v_rcp_f32_e32 v45, v20
	v_pk_mul_f32 v[40:41], v[42:43], v[40:41]
	v_and_b32_e32 v16, 0xffff0000, v19
	v_pk_mul_f32 v[26:27], v[46:47], v[14:15] op_sel_hi:[1,0]
	v_pk_mul_f32 v[34:35], v[34:35], v[14:15] op_sel_hi:[1,0]
	v_pk_fma_f32 v[26:27], v[2:3], v[26:27], v[6:7]
	v_pk_fma_f32 v[34:35], v[0:1], v[34:35], v[4:5]
	v_pk_mul_f32 v[28:29], v[44:45], v[28:29]
	s_nop 0
	v_pk_fma_f32 v[26:27], v[10:11], v[66:67], v[26:27] op_sel_hi:[0,1,1]
	v_pk_fma_f32 v[34:35], v[10:11], v[58:59], v[34:35] op_sel_hi:[0,1,1]
	v_pk_mul_f32 v[34:35], v[40:41], v[34:35]
	v_pk_mul_f32 v[26:27], v[28:29], v[26:27]
	v_cvt_pk_bf16_f32 v28, v34, v35
	v_cvt_pk_bf16_f32 v29, v26, v27
	global_store_dwordx2 v[36:37], v[28:29], off
	s_nop 0
	v_mov_b32_e32 v26, v112
	v_mov_b32_e32 v27, v113
	v_mov_b32_e32 v28, v114
	v_mov_b32_e32 v29, v115
	v_mov_b32_e32 v10, v116
	s_nop 0
	v_lshlrev_b64 v[34:35], 6, v[22:23]
	v_lshl_add_u64 v[34:35], s[4:5], 0, v[34:35]
	v_lshlrev_b64 v[22:23], 12, v[22:23]
	v_and_b32_e32 v14, 0xffff0000, v15
	v_and_b32_e32 v15, 0xffff0000, v17
	v_and_b32_e32 v17, 0xffff0000, v21
	v_lshl_add_u64 v[22:23], v[24:25], 0, v[22:23]
	s_nop 0
	v_lshlrev_b32_e32 v19, 16, v27
	v_lshlrev_b32_e32 v18, 16, v26
	v_and_b32_e32 v21, 0xffff0000, v27
	v_and_b32_e32 v20, 0xffff0000, v26
	s_nop 0
	v_lshlrev_b32_e32 v24, 16, v28
	v_and_b32_e32 v25, 0xffff0000, v28
	v_lshlrev_b32_e32 v26, 16, v29
	v_and_b32_e32 v27, 0xffff0000, v29
	v_pk_add_f32 v[28:29], v[18:19], v[20:21]
	v_mul_f32_e32 v33, 0xbfb8aa3b, v24
	v_add_f32_e32 v28, v28, v29
	v_mul_f32_e32 v34, 0xbfb8aa3b, v25
	v_mul_f32_e32 v35, 0xbfb8aa3b, v26
	v_add_f32_dpp v28, v28, v28 quad_perm:[1,0,3,2] row_mask:0xf bank_mask:0xf bound_ctrl:1
	v_mul_f32_e32 v36, 0xbfb8aa3b, v27
	v_exp_f32_e32 v29, v33
	v_add_f32_dpp v28, v28, v28 quad_perm:[2,3,0,1] row_mask:0xf bank_mask:0xf bound_ctrl:1
	v_exp_f32_e32 v33, v34
	v_exp_f32_e32 v34, v35
	v_add_f32_dpp v28, v28, v28 row_half_mirror row_mask:0xf bank_mask:0xf bound_ctrl:1
	v_exp_f32_e32 v35, v36
	v_add_f32_e32 v29, 1.0, v29
	v_add_f32_dpp v28, v28, v28 row_mirror row_mask:0xf bank_mask:0xf bound_ctrl:1
	v_fmac_f32_e32 v20, 0xbc800000, v28
	v_fmac_f32_e32 v21, 0xbc800000, v28
	v_fmac_f32_e32 v19, 0xbc800000, v28
	v_fmac_f32_e32 v18, 0xbc800000, v28
	v_mov_b32_e32 v36, v19
	v_mov_b32_e32 v37, v21
	v_mov_b32_e32 v19, v20
	v_pk_mul_f32 v[20:21], v[36:37], v[36:37]
	v_pk_mul_f32 v[38:39], v[18:19], v[18:19]
	v_add_f32_e32 v33, 1.0, v33
	v_pk_mov_b32 v[40:41], v[38:39], v[20:21] op_sel:[1,0]
	v_mov_b32_e32 v39, v21
	v_pk_add_f32 v[20:21], v[40:41], v[38:39]
	v_rcp_f32_e32 v28, v29
	v_add_f32_e32 v20, v20, v21
	v_rcp_f32_e32 v29, v33
	v_add_f32_e32 v34, 1.0, v34
	v_add_f32_dpp v20, v20, v20 quad_perm:[1,0,3,2] row_mask:0xf bank_mask:0xf bound_ctrl:1
	v_add_f32_e32 v35, 1.0, v35
	v_rcp_f32_e32 v34, v34
	v_add_f32_dpp v20, v20, v20 quad_perm:[2,3,0,1] row_mask:0xf bank_mask:0xf bound_ctrl:1
	v_rcp_f32_e32 v35, v35
	v_pk_mul_f32 v[24:25], v[28:29], v[24:25]
	v_add_f32_dpp v20, v20, v20 row_half_mirror row_mask:0xf bank_mask:0xf bound_ctrl:1
	v_pk_mul_f32 v[26:27], v[34:35], v[26:27]
	s_nop 0
	v_add_f32_dpp v20, v20, v20 row_mirror row_mask:0xf bank_mask:0xf bound_ctrl:1
	v_fmamk_f32 v20, v20, 0x3c800000, v32
	v_rsq_f32_e32 v20, v20
	s_nop 0
	v_pk_mul_f32 v[28:29], v[36:37], v[20:21] op_sel_hi:[1,0]
	v_pk_mul_f32 v[18:19], v[18:19], v[20:21] op_sel_hi:[1,0]
	v_pk_fma_f32 v[2:3], v[2:3], v[28:29], v[6:7]
	v_pk_fma_f32 v[0:1], v[0:1], v[18:19], v[4:5]
	s_nop 0
	v_pk_fma_f32 v[2:3], v[10:11], v[16:17], v[2:3] op_sel_hi:[0,1,1]
	v_pk_fma_f32 v[0:1], v[10:11], v[14:15], v[0:1] op_sel_hi:[0,1,1]
	v_pk_mul_f32 v[0:1], v[24:25], v[0:1]
	v_pk_mul_f32 v[2:3], v[26:27], v[2:3]
	v_cvt_pk_bf16_f32 v0, v0, v1
	v_cvt_pk_bf16_f32 v1, v2, v3
	global_store_dwordx2 v[22:23], v[0:1], off
	s_cbranch_scc0 .LBB0_640
